# stack of exact edits: 32-bit saddr store addressing, attention x+0 removal, FFT forward-loop write address batching
# speedup vs baseline: 1.0002x; 1.0002x over previous
; template <bool ZH> __device__ __forceinline__ void fft8192_r16x2(LAS f32x2* W0, LAS f32x2* W1, int tid) {
;     ...
;         { const int q = tid & (s - 1), p = tid >> sh;
;           const float fr = -(float)(p << sh) * (1.0f / 8192.0f);
;           c2 w1 = c2{__builtin_amdgcn_cosf(fr), __builtin_amdgcn_sinf(fr)};
;           asm volatile("s_nop 1" : "+v"(w1));
;           const int pb = fphys(q + ((16 * p) << sh));
;           dft16(v0); twid16(v0, w1);
.LBB0_597:
	s_lshl_b32 s19, 1, s3
	s_lshr_b32 s22, s19, 4
	v_ashrrev_i32_e32 v180, s3, v154
	s_add_i32 s19, s22, s19
	s_bfm_b32 s22, s3, 0
	v_lshlrev_b32_e32 v144, s3, v180
	v_and_b32_e32 v208, s22, v154
	v_lshlrev_b32_e32 v180, 4, v180
	v_lshl_add_u32 v180, v180, s3, v208
	v_ashrrev_i32_e32 v208, 4, v180
	v_add_u32_e32 v180, v208, v180
	s_waitcnt lgkmcnt(14)
	v_pk_add_f32 v[208:209], v[134:135], v[152:153]
	v_pk_add_f32 v[134:135], v[134:135], v[152:153] neg_lo:[0,1] neg_hi:[0,1]
	s_waitcnt lgkmcnt(11)
	v_pk_add_f32 v[152:153], v[132:133], v[150:151]
	v_pk_add_f32 v[132:133], v[132:133], v[150:151] neg_lo:[0,1] neg_hi:[0,1]
	v_pk_add_f32 v[150:151], v[208:209], v[152:153]
	v_pk_add_f32 v[152:153], v[208:209], v[152:153] neg_lo:[0,1] neg_hi:[0,1]
	v_pk_add_f32 v[208:209], v[134:135], v[132:133] op_sel:[0,1] op_sel_hi:[1,0] neg_hi:[0,1]
	v_pk_add_f32 v[216:217], v[134:135], v[132:133] op_sel:[0,1] op_sel_hi:[1,0] neg_lo:[0,1]
	v_pk_add_f32 v[132:133], v[130:131], v[148:149]
	v_pk_add_f32 v[130:131], v[130:131], v[148:149] neg_lo:[0,1] neg_hi:[0,1]
	s_waitcnt lgkmcnt(10)
	v_pk_add_f32 v[134:135], v[128:129], v[146:147]
	v_pk_add_f32 v[128:129], v[128:129], v[146:147] neg_lo:[0,1] neg_hi:[0,1]
	v_pk_add_f32 v[146:147], v[132:133], v[134:135]
	v_pk_add_f32 v[132:133], v[132:133], v[134:135] neg_lo:[0,1] neg_hi:[0,1]
	v_pk_add_f32 v[134:135], v[130:131], v[128:129] op_sel:[0,1] op_sel_hi:[1,0] neg_hi:[0,1]
	v_pk_add_f32 v[148:149], v[130:131], v[128:129] op_sel:[0,1] op_sel_hi:[1,0] neg_lo:[0,1]
	v_pk_add_f32 v[128:129], v[126:127], v[142:143]
	v_pk_add_f32 v[126:127], v[126:127], v[142:143] neg_lo:[0,1] neg_hi:[0,1]
	s_waitcnt lgkmcnt(9)
	v_pk_add_f32 v[130:131], v[124:125], v[140:141]
	v_pk_add_f32 v[124:125], v[124:125], v[140:141] neg_lo:[0,1] neg_hi:[0,1]
	v_pk_add_f32 v[140:141], v[128:129], v[130:131]
	v_pk_add_f32 v[128:129], v[128:129], v[130:131] neg_lo:[0,1] neg_hi:[0,1]
	v_pk_add_f32 v[130:131], v[126:127], v[124:125] op_sel:[0,1] op_sel_hi:[1,0] neg_hi:[0,1]
	v_pk_add_f32 v[142:143], v[126:127], v[124:125] op_sel:[0,1] op_sel_hi:[1,0] neg_lo:[0,1]
	v_pk_add_f32 v[124:125], v[122:123], v[138:139]
	v_pk_add_f32 v[122:123], v[122:123], v[138:139] neg_lo:[0,1] neg_hi:[0,1]
	s_waitcnt lgkmcnt(8)
	v_pk_add_f32 v[126:127], v[120:121], v[136:137]
	v_pk_add_f32 v[120:121], v[120:121], v[136:137] neg_lo:[0,1] neg_hi:[0,1]
	v_pk_add_f32 v[136:137], v[124:125], v[126:127]
	v_pk_add_f32 v[124:125], v[124:125], v[126:127] neg_lo:[0,1] neg_hi:[0,1]
	v_pk_add_f32 v[126:127], v[122:123], v[120:121] op_sel:[0,1] op_sel_hi:[1,0] neg_hi:[0,1]
	v_pk_add_f32 v[138:139], v[122:123], v[120:121] op_sel:[0,1] op_sel_hi:[1,0] neg_lo:[0,1]
	v_mov_b64_e32 v[120:121], s[64:65]
	v_pk_mul_f32 v[122:123], v[134:135], v[120:121] op_sel_hi:[0,1]
	v_cvt_f32_i32_e32 v144, v144
	v_pk_fma_f32 v[218:219], v[134:135], v[120:121], v[122:123] op_sel:[1,1,0] op_sel_hi:[1,0,1] neg_lo:[0,1,0]
	v_pk_add_f32 v[122:123], v[130:131], v[130:131] op_sel:[0,1] op_sel_hi:[1,0] neg_hi:[0,1]
	v_mov_b64_e32 v[130:131], s[66:67]
	v_pk_mul_f32 v[134:135], v[126:127], v[130:131] op_sel_hi:[0,1]
	s_mov_b32 s22, s67
	v_pk_fma_f32 v[220:221], v[126:127], v[130:131], v[134:135] op_sel:[1,1,0] op_sel_hi:[1,0,1] neg_lo:[0,1,0]
	v_pk_add_f32 v[126:127], v[132:133], v[132:133] op_sel:[0,1] op_sel_hi:[1,0] neg_hi:[0,1]
	v_xor_b32_e32 v133, 0x80000000, v128
	v_mov_b32_e32 v132, v129
	v_pk_add_f32 v[128:129], v[124:125], v[124:125] op_sel:[0,1] op_sel_hi:[1,0] neg_lo:[0,1]
	s_mov_b32 s23, s66
	v_pk_mul_f32 v[124:125], v[128:129], s[80:81] op_sel_hi:[1,0]
	v_pk_mul_f32 v[128:129], v[148:149], v[130:131] op_sel_hi:[0,1]
	v_mul_f32_e32 v145, 0xb9000000, v144
	v_pk_fma_f32 v[134:135], v[148:149], v[130:131], v[128:129] op_sel:[1,1,0] op_sel_hi:[1,0,1] neg_lo:[0,1,0]
	v_pk_add_f32 v[128:129], v[142:143], v[142:143] op_sel:[0,1] op_sel_hi:[1,0] neg_lo:[0,1]
	v_mov_b64_e32 v[142:143], s[22:23]
	v_pk_mul_f32 v[148:149], v[138:139], v[142:143] op_sel_hi:[0,1]
	v_cos_f32_e32 v144, v145
	v_pk_fma_f32 v[224:225], v[138:139], v[142:143], v[148:149] op_sel:[1,1,0] op_sel_hi:[1,0,1] neg_lo:[0,1,0]
	v_pk_add_f32 v[138:139], v[150:151], v[140:141]
	v_pk_add_f32 v[140:141], v[150:151], v[140:141] neg_lo:[0,1] neg_hi:[0,1]
	v_pk_add_f32 v[148:149], v[146:147], v[136:137]
	v_pk_add_f32 v[136:137], v[146:147], v[136:137] neg_lo:[0,1] neg_hi:[0,1]
	v_pk_add_f32 v[146:147], v[138:139], v[148:149]
	v_pk_add_f32 v[138:139], v[138:139], v[148:149] neg_lo:[0,1] neg_hi:[0,1]
	v_pk_add_f32 v[148:149], v[140:141], v[136:137] op_sel:[0,1] op_sel_hi:[1,0] neg_hi:[0,1]
	v_pk_add_f32 v[150:151], v[140:141], v[136:137] op_sel:[0,1] op_sel_hi:[1,0] neg_lo:[0,1]
	v_pk_fma_f32 v[136:137], v[122:123], s[78:79], v[208:209] op_sel_hi:[1,0,1]
	v_pk_fma_f32 v[122:123], v[122:123], s[78:79], v[208:209] op_sel_hi:[1,0,1] neg_lo:[1,0,0] neg_hi:[1,0,0]
	v_pk_add_f32 v[140:141], v[218:219], v[220:221]
	v_pk_add_f32 v[208:209], v[218:219], v[220:221] neg_lo:[0,1] neg_hi:[0,1]
	v_pk_add_f32 v[218:219], v[136:137], v[140:141]
	v_pk_add_f32 v[136:137], v[136:137], v[140:141] neg_lo:[0,1] neg_hi:[0,1]
	v_pk_add_f32 v[140:141], v[122:123], v[208:209] op_sel:[0,1] op_sel_hi:[1,0] neg_hi:[0,1]
	v_pk_add_f32 v[220:221], v[122:123], v[208:209] op_sel:[0,1] op_sel_hi:[1,0] neg_lo:[0,1]
	v_pk_add_f32 v[122:123], v[152:153], v[132:133]
	v_pk_add_f32 v[132:133], v[152:153], v[132:133] neg_lo:[0,1] neg_hi:[0,1]
	v_pk_fma_f32 v[152:153], v[126:127], s[78:79], v[124:125] op_sel_hi:[1,0,1]
	v_pk_fma_f32 v[124:125], v[126:127], s[78:79], v[124:125] op_sel_hi:[1,0,1] neg_lo:[0,0,1] neg_hi:[0,0,1]
	v_sin_f32_e32 v145, v145
	v_pk_add_f32 v[126:127], v[122:123], v[152:153]
	v_pk_add_f32 v[122:123], v[122:123], v[152:153] neg_lo:[0,1] neg_hi:[0,1]
	v_pk_add_f32 v[152:153], v[132:133], v[124:125] op_sel:[0,1] op_sel_hi:[1,0] neg_hi:[0,1]
	v_pk_add_f32 v[208:209], v[132:133], v[124:125] op_sel:[0,1] op_sel_hi:[1,0] neg_lo:[0,1]
	v_pk_fma_f32 v[124:125], v[128:129], s[80:81], v[216:217] op_sel_hi:[1,0,1]
	v_pk_fma_f32 v[128:129], v[128:129], s[80:81], v[216:217] op_sel_hi:[1,0,1] neg_lo:[1,0,0] neg_hi:[1,0,0]
	v_pk_add_f32 v[132:133], v[134:135], v[224:225]
	s_waitcnt lgkmcnt(0)
	s_barrier
; template <bool ZH> __device__ __forceinline__ void fft8192_r16x2(LAS f32x2* W0, LAS f32x2* W1, int tid) {
;     ...
;           dft16(v0); twid16(v0, w1);
; #pragma unroll
;           for (int r = 0; r < 16; ++r) W0[pb + r * strd] = v0[DFT16_SLOT(r)];
	s_nop 1
	v_pk_add_f32 v[134:135], v[134:135], v[224:225] neg_lo:[0,1] neg_hi:[0,1]
	v_pk_add_f32 v[216:217], v[124:125], v[132:133]
	v_pk_add_f32 v[124:125], v[124:125], v[132:133] neg_lo:[0,1] neg_hi:[0,1]
	v_pk_add_f32 v[132:133], v[128:129], v[134:135] op_sel:[0,1] op_sel_hi:[1,0] neg_hi:[0,1]
	v_pk_add_f32 v[224:225], v[128:129], v[134:135] op_sel:[0,1] op_sel_hi:[1,0] neg_lo:[0,1]
	v_pk_mul_f32 v[128:129], v[218:219], v[144:145] op_sel_hi:[0,1]
	v_lshl_add_u32 v180, v180, 3, 0
	v_pk_fma_f32 v[134:135], v[218:219], v[144:145], v[128:129] op_sel:[1,1,0] op_sel_hi:[1,0,1] neg_lo:[0,1,0]
	v_pk_mul_f32 v[128:129], v[144:145], v[144:145] op_sel_hi:[0,1]
	s_lshl_b32 s19, s19, 3
	v_pk_fma_f32 v[218:219], v[144:145], v[144:145], v[128:129] op_sel:[1,1,0] op_sel_hi:[1,0,1] neg_lo:[0,1,0]
	ds_write_b64 v180, v[146:147]
	v_pk_mul_f32 v[128:129], v[126:127], v[218:219] op_sel_hi:[0,1]
	s_add_i32 s3, s3, 4
	v_pk_fma_f32 v[226:227], v[126:127], v[218:219], v[128:129] op_sel:[1,1,0] op_sel_hi:[1,0,1] neg_lo:[0,1,0]
	v_pk_mul_f32 v[126:127], v[218:219], v[144:145] op_sel_hi:[0,1]
	s_cmp_lg_u32 s3, 12
	v_pk_fma_f32 v[128:129], v[218:219], v[144:145], v[126:127] op_sel:[1,1,0] op_sel_hi:[1,0,1] neg_lo:[0,1,0]
	s_nop 0
	v_pk_mul_f32 v[126:127], v[216:217], v[128:129] op_sel_hi:[0,1]
	s_nop 0
	v_pk_fma_f32 v[230:231], v[216:217], v[128:129], v[126:127] op_sel:[1,1,0] op_sel_hi:[1,0,1] neg_lo:[0,1,0]
	v_pk_mul_f32 v[126:127], v[128:129], v[144:145] op_sel_hi:[0,1]
	s_nop 0
	v_pk_fma_f32 v[216:217], v[128:129], v[144:145], v[126:127] op_sel:[1,1,0] op_sel_hi:[1,0,1] neg_lo:[0,1,0]
	s_nop 0
	v_pk_mul_f32 v[126:127], v[148:149], v[216:217] op_sel_hi:[0,1]
	s_nop 0
	v_pk_fma_f32 v[232:233], v[148:149], v[216:217], v[126:127] op_sel:[1,1,0] op_sel_hi:[1,0,1] neg_lo:[0,1,0]
	v_pk_mul_f32 v[126:127], v[216:217], v[144:145] op_sel_hi:[0,1]
	s_nop 0
	v_pk_fma_f32 v[148:149], v[216:217], v[144:145], v[126:127] op_sel:[1,1,0] op_sel_hi:[1,0,1] neg_lo:[0,1,0]
	s_nop 0
	v_pk_mul_f32 v[126:127], v[140:141], v[148:149] op_sel_hi:[0,1]
	s_nop 0
	v_pk_fma_f32 v[234:235], v[140:141], v[148:149], v[126:127] op_sel:[1,1,0] op_sel_hi:[1,0,1] neg_lo:[0,1,0]
	v_pk_mul_f32 v[126:127], v[148:149], v[144:145] op_sel_hi:[0,1]
	s_nop 0
	v_pk_fma_f32 v[140:141], v[148:149], v[144:145], v[126:127] op_sel:[1,1,0] op_sel_hi:[1,0,1] neg_lo:[0,1,0]
	s_nop 0
	v_pk_mul_f32 v[126:127], v[152:153], v[140:141] op_sel_hi:[0,1]
	s_nop 0
	v_pk_fma_f32 v[236:237], v[152:153], v[140:141], v[126:127] op_sel:[1,1,0] op_sel_hi:[1,0,1] neg_lo:[0,1,0]
	v_pk_mul_f32 v[126:127], v[140:141], v[144:145] op_sel_hi:[0,1]
	s_nop 0
	v_pk_fma_f32 v[152:153], v[140:141], v[144:145], v[126:127] op_sel:[1,1,0] op_sel_hi:[1,0,1] neg_lo:[0,1,0]
	s_nop 0
	v_pk_mul_f32 v[126:127], v[132:133], v[152:153] op_sel_hi:[0,1]
	s_nop 0
	v_pk_fma_f32 v[238:239], v[132:133], v[152:153], v[126:127] op_sel:[1,1,0] op_sel_hi:[1,0,1] neg_lo:[0,1,0]
	v_pk_mul_f32 v[126:127], v[152:153], v[144:145] op_sel_hi:[0,1]
	s_nop 0
	v_pk_fma_f32 v[132:133], v[152:153], v[144:145], v[126:127] op_sel:[1,1,0] op_sel_hi:[1,0,1] neg_lo:[0,1,0]
	s_nop 0
	v_pk_mul_f32 v[126:127], v[138:139], v[132:133] op_sel_hi:[0,1]
	s_nop 0
	v_pk_fma_f32 v[240:241], v[138:139], v[132:133], v[126:127] op_sel:[1,1,0] op_sel_hi:[1,0,1] neg_lo:[0,1,0]
	v_pk_mul_f32 v[126:127], v[132:133], v[144:145] op_sel_hi:[0,1]
	s_nop 0
	v_pk_fma_f32 v[138:139], v[132:133], v[144:145], v[126:127] op_sel:[1,1,0] op_sel_hi:[1,0,1] neg_lo:[0,1,0]
	s_nop 0
	v_pk_mul_f32 v[126:127], v[136:137], v[138:139] op_sel_hi:[0,1]
	s_nop 0
	v_pk_fma_f32 v[242:243], v[136:137], v[138:139], v[126:127] op_sel:[1,1,0] op_sel_hi:[1,0,1] neg_lo:[0,1,0]
	v_pk_mul_f32 v[126:127], v[138:139], v[144:145] op_sel_hi:[0,1]
	s_nop 0
	v_pk_fma_f32 v[136:137], v[138:139], v[144:145], v[126:127] op_sel:[1,1,0] op_sel_hi:[1,0,1] neg_lo:[0,1,0]
	s_nop 0
	v_pk_mul_f32 v[126:127], v[122:123], v[136:137] op_sel_hi:[0,1]
	s_nop 0
	v_pk_fma_f32 v[244:245], v[122:123], v[136:137], v[126:127] op_sel:[1,1,0] op_sel_hi:[1,0,1] neg_lo:[0,1,0]
	v_pk_mul_f32 v[122:123], v[136:137], v[144:145] op_sel_hi:[0,1]
	s_nop 0
	v_pk_fma_f32 v[126:127], v[136:137], v[144:145], v[122:123] op_sel:[1,1,0] op_sel_hi:[1,0,1] neg_lo:[0,1,0]
	s_nop 0
	v_pk_mul_f32 v[122:123], v[124:125], v[126:127] op_sel_hi:[0,1]
	s_nop 0
	v_pk_fma_f32 v[246:247], v[124:125], v[126:127], v[122:123] op_sel:[1,1,0] op_sel_hi:[1,0,1] neg_lo:[0,1,0]
	v_pk_mul_f32 v[122:123], v[126:127], v[144:145] op_sel_hi:[0,1]
	s_nop 0
	v_pk_fma_f32 v[124:125], v[126:127], v[144:145], v[122:123] op_sel:[1,1,0] op_sel_hi:[1,0,1] neg_lo:[0,1,0]
	s_nop 0
	v_pk_mul_f32 v[122:123], v[150:151], v[124:125] op_sel_hi:[0,1]
	s_nop 0
	v_pk_fma_f32 v[248:249], v[150:151], v[124:125], v[122:123] op_sel:[1,1,0] op_sel_hi:[1,0,1] neg_lo:[0,1,0]
	v_pk_mul_f32 v[122:123], v[124:125], v[144:145] op_sel_hi:[0,1]
	s_nop 0
	v_pk_fma_f32 v[150:151], v[124:125], v[144:145], v[122:123] op_sel:[1,1,0] op_sel_hi:[1,0,1] neg_lo:[0,1,0]
	s_nop 0
	v_pk_mul_f32 v[122:123], v[220:221], v[150:151] op_sel_hi:[0,1]
	s_nop 0
	v_pk_fma_f32 v[250:251], v[220:221], v[150:151], v[122:123] op_sel:[1,1,0] op_sel_hi:[1,0,1] neg_lo:[0,1,0]
	v_pk_mul_f32 v[122:123], v[150:151], v[144:145] op_sel_hi:[0,1]
	s_nop 0
	v_pk_fma_f32 v[220:221], v[150:151], v[144:145], v[122:123] op_sel:[1,1,0] op_sel_hi:[1,0,1] neg_lo:[0,1,0]
	s_nop 0
	v_pk_mul_f32 v[122:123], v[208:209], v[220:221] op_sel_hi:[0,1]
	s_nop 0
	v_pk_fma_f32 v[252:253], v[208:209], v[220:221], v[122:123] op_sel:[1,1,0] op_sel_hi:[1,0,1] neg_lo:[0,1,0]
	v_pk_mul_f32 v[122:123], v[220:221], v[144:145] op_sel_hi:[0,1]
	s_nop 0
	v_pk_fma_f32 v[208:209], v[220:221], v[144:145], v[122:123] op_sel:[1,1,0] op_sel_hi:[1,0,1] neg_lo:[0,1,0]
	s_nop 0
	v_pk_mul_f32 v[122:123], v[224:225], v[208:209] op_sel_hi:[0,1]
	s_nop 0
	v_pk_fma_f32 v[214:215], v[224:225], v[208:209], v[122:123] op_sel:[1,1,0] op_sel_hi:[1,0,1] neg_lo:[0,1,0]
	v_add_u32_e32 v122, s19, v180
	ds_write_b64 v122, v[134:135]
	v_mad_u32_u24 v134, s19, 2, v180
	v_mad_u32_u24 v135, s19, 3, v180
	ds_write_b64 v134, v[226:227]
	ds_write_b64 v135, v[230:231]
	v_mad_u32_u24 v226, s19, 4, v180
	v_mad_u32_u24 v227, s19, 5, v180
	v_mad_u32_u24 v230, s19, 6, v180
	v_mad_u32_u24 v231, s19, 7, v180
	ds_write_b64 v226, v[232:233]
	ds_write_b64 v227, v[234:235]
	ds_write_b64 v230, v[236:237]
	ds_write_b64 v231, v[238:239]
	v_mad_u32_u24 v232, s19, 8, v180
	v_mad_u32_u24 v233, s19, 9, v180
	v_mad_u32_u24 v234, s19, 10, v180
	v_mad_u32_u24 v235, s19, 11, v180
	v_mad_u32_u24 v236, s19, 12, v180
	v_mad_u32_u24 v237, s19, 13, v180
	v_mad_u32_u24 v238, s19, 14, v180
	v_mad_u32_u24 v239, s19, 15, v180
	ds_write_b64 v232, v[240:241]
	ds_write_b64 v233, v[242:243]
	ds_write_b64 v234, v[244:245]
	ds_write_b64 v235, v[246:247]
	ds_write_b64 v236, v[248:249]
	ds_write_b64 v237, v[250:251]
	ds_write_b64 v238, v[252:253]
	ds_write_b64 v239, v[214:215]
	s_waitcnt lgkmcnt(14)
; template <bool ZH> __device__ __forceinline__ void fft8192_r16x2(LAS f32x2* W0, LAS f32x2* W1, int tid) {
;     ...
;           dft16(v1); twid16(v1, w1);
	v_pk_add_f32 v[122:123], v[100:101], v[116:117]
	v_pk_add_f32 v[100:101], v[100:101], v[116:117] neg_lo:[0,1] neg_hi:[0,1]
	v_pk_add_f32 v[116:117], v[102:103], v[118:119]
	v_pk_add_f32 v[102:103], v[102:103], v[118:119] neg_lo:[0,1] neg_hi:[0,1]
	v_pk_add_f32 v[118:119], v[116:117], v[122:123]
	v_pk_add_f32 v[116:117], v[122:123], v[116:117] neg_lo:[0,1] neg_hi:[0,1]
	v_pk_add_f32 v[122:123], v[100:101], v[102:103] op_sel:[0,1] op_sel_hi:[1,0] neg_hi:[0,1]
	v_pk_add_f32 v[134:135], v[100:101], v[102:103] op_sel:[0,1] op_sel_hi:[1,0] neg_lo:[0,1]
	v_pk_add_f32 v[100:101], v[96:97], v[112:113]
	v_pk_add_f32 v[96:97], v[96:97], v[112:113] neg_lo:[0,1] neg_hi:[0,1]
	v_pk_add_f32 v[102:103], v[98:99], v[114:115]
	v_pk_add_f32 v[98:99], v[98:99], v[114:115] neg_lo:[0,1] neg_hi:[0,1]
	v_pk_add_f32 v[112:113], v[102:103], v[100:101]
	v_pk_add_f32 v[100:101], v[100:101], v[102:103] neg_lo:[0,1] neg_hi:[0,1]
	v_pk_add_f32 v[102:103], v[96:97], v[98:99] op_sel:[0,1] op_sel_hi:[1,0] neg_hi:[0,1]
	v_pk_add_f32 v[114:115], v[96:97], v[98:99] op_sel:[0,1] op_sel_hi:[1,0] neg_lo:[0,1]
	v_pk_add_f32 v[96:97], v[92:93], v[108:109]
	v_pk_add_f32 v[92:93], v[92:93], v[108:109] neg_lo:[0,1] neg_hi:[0,1]
	v_pk_add_f32 v[98:99], v[94:95], v[110:111]
	v_pk_add_f32 v[94:95], v[94:95], v[110:111] neg_lo:[0,1] neg_hi:[0,1]
	v_pk_add_f32 v[108:109], v[98:99], v[96:97]
	v_pk_add_f32 v[96:97], v[96:97], v[98:99] neg_lo:[0,1] neg_hi:[0,1]
	v_pk_add_f32 v[98:99], v[92:93], v[94:95] op_sel:[0,1] op_sel_hi:[1,0] neg_hi:[0,1]
	v_pk_add_f32 v[110:111], v[92:93], v[94:95] op_sel:[0,1] op_sel_hi:[1,0] neg_lo:[0,1]
	v_pk_add_f32 v[92:93], v[88:89], v[104:105]
	v_pk_add_f32 v[88:89], v[88:89], v[104:105] neg_lo:[0,1] neg_hi:[0,1]
	v_pk_add_f32 v[94:95], v[90:91], v[106:107]
	v_pk_add_f32 v[90:91], v[90:91], v[106:107] neg_lo:[0,1] neg_hi:[0,1]
	v_pk_add_f32 v[104:105], v[94:95], v[92:93]
	v_pk_add_f32 v[92:93], v[92:93], v[94:95] neg_lo:[0,1] neg_hi:[0,1]
	v_pk_add_f32 v[94:95], v[88:89], v[90:91] op_sel:[0,1] op_sel_hi:[1,0] neg_hi:[0,1]
	v_pk_add_f32 v[106:107], v[88:89], v[90:91] op_sel:[0,1] op_sel_hi:[1,0] neg_lo:[0,1]
	v_pk_mul_f32 v[88:89], v[102:103], v[120:121] op_sel_hi:[0,1]
	s_nop 0
	v_pk_fma_f32 v[90:91], v[102:103], v[120:121], v[88:89] op_sel:[1,1,0] op_sel_hi:[1,0,1] neg_lo:[0,1,0]
	v_pk_add_f32 v[88:89], v[98:99], v[98:99] op_sel:[0,1] op_sel_hi:[1,0] neg_hi:[0,1]
	v_pk_mul_f32 v[98:99], v[94:95], v[130:131] op_sel_hi:[0,1]
	s_nop 0
	v_pk_fma_f32 v[102:103], v[94:95], v[130:131], v[98:99] op_sel:[1,1,0] op_sel_hi:[1,0,1] neg_lo:[0,1,0]
	v_xor_b32_e32 v99, 0x80000000, v96
	v_mov_b32_e32 v98, v97
	v_pk_add_f32 v[96:97], v[92:93], v[92:93] op_sel:[0,1] op_sel_hi:[1,0] neg_lo:[0,1]
	v_pk_add_f32 v[94:95], v[100:101], v[100:101] op_sel:[0,1] op_sel_hi:[1,0] neg_hi:[0,1]
	s_nop 0
	v_pk_mul_f32 v[92:93], v[96:97], s[80:81] op_sel_hi:[1,0]
	v_pk_mul_f32 v[96:97], v[114:115], v[130:131] op_sel_hi:[0,1]
	s_nop 0
	v_pk_fma_f32 v[100:101], v[114:115], v[130:131], v[96:97] op_sel:[1,1,0] op_sel_hi:[1,0,1] neg_lo:[0,1,0]
	v_pk_add_f32 v[96:97], v[110:111], v[110:111] op_sel:[0,1] op_sel_hi:[1,0] neg_lo:[0,1]
	v_pk_mul_f32 v[110:111], v[106:107], v[142:143] op_sel_hi:[0,1]
	s_nop 0
	v_pk_fma_f32 v[114:115], v[106:107], v[142:143], v[110:111] op_sel:[1,1,0] op_sel_hi:[1,0,1] neg_lo:[0,1,0]
	v_pk_add_f32 v[106:107], v[108:109], v[118:119]
	v_pk_add_f32 v[108:109], v[118:119], v[108:109] neg_lo:[0,1] neg_hi:[0,1]
	v_pk_add_f32 v[110:111], v[104:105], v[112:113]
	v_pk_add_f32 v[104:105], v[112:113], v[104:105] neg_lo:[0,1] neg_hi:[0,1]
	v_pk_add_f32 v[112:113], v[110:111], v[106:107]
	v_pk_add_f32 v[106:107], v[106:107], v[110:111] neg_lo:[0,1] neg_hi:[0,1]
	v_pk_add_f32 v[110:111], v[108:109], v[104:105] op_sel:[0,1] op_sel_hi:[1,0] neg_hi:[0,1]
	v_pk_add_f32 v[118:119], v[108:109], v[104:105] op_sel:[0,1] op_sel_hi:[1,0] neg_lo:[0,1]
	v_pk_fma_f32 v[104:105], v[88:89], s[78:79], v[122:123] op_sel_hi:[1,0,1]
	v_pk_fma_f32 v[88:89], v[88:89], s[78:79], v[122:123] op_sel_hi:[1,0,1] neg_lo:[1,0,0] neg_hi:[1,0,0]
	v_pk_add_f32 v[108:109], v[90:91], v[102:103]
	v_pk_add_f32 v[90:91], v[90:91], v[102:103] neg_lo:[0,1] neg_hi:[0,1]
	v_pk_add_f32 v[102:103], v[104:105], v[108:109]
	v_pk_add_f32 v[104:105], v[104:105], v[108:109] neg_lo:[0,1] neg_hi:[0,1]
	v_pk_add_f32 v[108:109], v[88:89], v[90:91] op_sel:[0,1] op_sel_hi:[1,0] neg_hi:[0,1]
	v_pk_add_f32 v[120:121], v[88:89], v[90:91] op_sel:[0,1] op_sel_hi:[1,0] neg_lo:[0,1]
	v_pk_add_f32 v[88:89], v[116:117], v[98:99]
	v_pk_add_f32 v[90:91], v[116:117], v[98:99] neg_lo:[0,1] neg_hi:[0,1]
	v_pk_fma_f32 v[98:99], v[94:95], s[78:79], v[92:93] op_sel_hi:[1,0,1]
; template <bool ZH> __device__ __forceinline__ void fft8192_r16x2(LAS f32x2* W0, LAS f32x2* W1, int tid) {
;     ...
;           dft16(v1); twid16(v1, w1);
; #pragma unroll
;           for (int r = 0; r < 16; ++r) W1[pb + r * strd] = v1[DFT16_SLOT(r)]; }
	v_pk_fma_f32 v[92:93], v[94:95], s[78:79], v[92:93] op_sel_hi:[1,0,1] neg_lo:[0,0,1] neg_hi:[0,0,1]
	v_pk_add_f32 v[94:95], v[88:89], v[98:99]
	v_pk_add_f32 v[88:89], v[88:89], v[98:99] neg_lo:[0,1] neg_hi:[0,1]
	v_pk_add_f32 v[98:99], v[90:91], v[92:93] op_sel:[0,1] op_sel_hi:[1,0] neg_hi:[0,1]
	v_pk_add_f32 v[116:117], v[90:91], v[92:93] op_sel:[0,1] op_sel_hi:[1,0] neg_lo:[0,1]
	v_pk_fma_f32 v[90:91], v[96:97], s[80:81], v[134:135] op_sel_hi:[1,0,1]
	v_pk_fma_f32 v[92:93], v[96:97], s[80:81], v[134:135] op_sel_hi:[1,0,1] neg_lo:[1,0,0] neg_hi:[1,0,0]
	v_pk_add_f32 v[96:97], v[100:101], v[114:115]
	v_pk_add_f32 v[100:101], v[100:101], v[114:115] neg_lo:[0,1] neg_hi:[0,1]
	v_pk_add_f32 v[114:115], v[90:91], v[96:97]
	v_pk_add_f32 v[90:91], v[90:91], v[96:97] neg_lo:[0,1] neg_hi:[0,1]
	v_pk_add_f32 v[96:97], v[92:93], v[100:101] op_sel:[0,1] op_sel_hi:[1,0] neg_hi:[0,1]
	v_pk_add_f32 v[122:123], v[92:93], v[100:101] op_sel:[0,1] op_sel_hi:[1,0] neg_lo:[0,1]
	v_pk_mul_f32 v[92:93], v[102:103], v[144:145] op_sel_hi:[0,1]
	s_nop 0
	v_pk_fma_f32 v[100:101], v[102:103], v[144:145], v[92:93] op_sel:[1,1,0] op_sel_hi:[1,0,1] neg_lo:[0,1,0]
	v_pk_mul_f32 v[92:93], v[94:95], v[218:219] op_sel_hi:[0,1]
	s_nop 0
	v_pk_fma_f32 v[102:103], v[94:95], v[218:219], v[92:93] op_sel:[1,1,0] op_sel_hi:[1,0,1] neg_lo:[0,1,0]
	v_pk_mul_f32 v[92:93], v[114:115], v[128:129] op_sel_hi:[0,1]
	s_nop 0
	v_pk_fma_f32 v[94:95], v[114:115], v[128:129], v[92:93] op_sel:[1,1,0] op_sel_hi:[1,0,1] neg_lo:[0,1,0]
	v_pk_mul_f32 v[92:93], v[110:111], v[216:217] op_sel_hi:[0,1]
	s_nop 0
	v_pk_fma_f32 v[114:115], v[110:111], v[216:217], v[92:93] op_sel:[1,1,0] op_sel_hi:[1,0,1] neg_lo:[0,1,0]
	v_pk_mul_f32 v[92:93], v[108:109], v[148:149] op_sel_hi:[0,1]
	s_nop 0
	v_pk_fma_f32 v[110:111], v[108:109], v[148:149], v[92:93] op_sel:[1,1,0] op_sel_hi:[1,0,1] neg_lo:[0,1,0]
	v_pk_mul_f32 v[92:93], v[98:99], v[140:141] op_sel_hi:[0,1]
	s_nop 0
	v_pk_fma_f32 v[108:109], v[98:99], v[140:141], v[92:93] op_sel:[1,1,0] op_sel_hi:[1,0,1] neg_lo:[0,1,0]
	v_pk_mul_f32 v[92:93], v[96:97], v[152:153] op_sel_hi:[0,1]
	s_nop 0
	v_pk_fma_f32 v[98:99], v[96:97], v[152:153], v[92:93] op_sel:[1,1,0] op_sel_hi:[1,0,1] neg_lo:[0,1,0]
	v_pk_mul_f32 v[92:93], v[106:107], v[132:133] op_sel_hi:[0,1]
	s_nop 0
	v_pk_fma_f32 v[96:97], v[106:107], v[132:133], v[92:93] op_sel:[1,1,0] op_sel_hi:[1,0,1] neg_lo:[0,1,0]
	v_pk_mul_f32 v[92:93], v[104:105], v[138:139] op_sel_hi:[0,1]
	s_nop 0
	v_pk_fma_f32 v[106:107], v[104:105], v[138:139], v[92:93] op_sel:[1,1,0] op_sel_hi:[1,0,1] neg_lo:[0,1,0]
	v_pk_mul_f32 v[92:93], v[88:89], v[136:137] op_sel_hi:[0,1]
	s_nop 0
	v_pk_fma_f32 v[104:105], v[88:89], v[136:137], v[92:93] op_sel:[1,1,0] op_sel_hi:[1,0,1] neg_lo:[0,1,0]
	v_pk_mul_f32 v[88:89], v[90:91], v[126:127] op_sel_hi:[0,1]
	s_nop 0
	v_pk_fma_f32 v[92:93], v[90:91], v[126:127], v[88:89] op_sel:[1,1,0] op_sel_hi:[1,0,1] neg_lo:[0,1,0]
	v_pk_mul_f32 v[88:89], v[118:119], v[124:125] op_sel_hi:[0,1]
	s_nop 0
	v_pk_fma_f32 v[90:91], v[118:119], v[124:125], v[88:89] op_sel:[1,1,0] op_sel_hi:[1,0,1] neg_lo:[0,1,0]
	v_pk_mul_f32 v[88:89], v[120:121], v[150:151] op_sel_hi:[0,1]
	s_nop 0
	v_pk_fma_f32 v[118:119], v[120:121], v[150:151], v[88:89] op_sel:[1,1,0] op_sel_hi:[1,0,1] neg_lo:[0,1,0]
	v_pk_mul_f32 v[88:89], v[116:117], v[220:221] op_sel_hi:[0,1]
	s_nop 0
	v_pk_fma_f32 v[120:121], v[116:117], v[220:221], v[88:89] op_sel:[1,1,0] op_sel_hi:[1,0,1] neg_lo:[0,1,0]
	v_pk_mul_f32 v[88:89], v[122:123], v[208:209] op_sel_hi:[0,1]
	s_nop 0
	v_pk_fma_f32 v[116:117], v[122:123], v[208:209], v[88:89] op_sel:[1,1,0] op_sel_hi:[1,0,1] neg_lo:[0,1,0]
	v_add_u32_e32 v88, 0x11000, v180
	ds_write_b64 v88, v[112:113]
	v_mad_u32_u24 v112, s19, 1, v88
	v_mad_u32_u24 v113, s19, 2, v88
	ds_write_b64 v112, v[100:101]
	ds_write_b64 v113, v[102:103]
	v_mad_u32_u24 v100, s19, 3, v88
	v_mad_u32_u24 v101, s19, 4, v88
	v_mad_u32_u24 v102, s19, 5, v88
	v_mad_u32_u24 v103, s19, 6, v88
	ds_write_b64 v100, v[94:95]
	ds_write_b64 v101, v[114:115]
	ds_write_b64 v102, v[110:111]
	ds_write_b64 v103, v[108:109]
	v_mad_u32_u24 v94, s19, 7, v88
	v_mad_u32_u24 v95, s19, 8, v88
	v_mad_u32_u24 v114, s19, 9, v88
	v_mad_u32_u24 v115, s19, 10, v88
	v_mad_u32_u24 v110, s19, 11, v88
	v_mad_u32_u24 v111, s19, 12, v88
	v_mad_u32_u24 v108, s19, 13, v88
	v_mad_u32_u24 v109, s19, 14, v88
	ds_write_b64 v94, v[98:99]
	ds_write_b64 v95, v[96:97]
	ds_write_b64 v114, v[106:107]
	ds_write_b64 v115, v[104:105]
	ds_write_b64 v110, v[92:93]
	ds_write_b64 v111, v[90:91]
	ds_write_b64 v108, v[118:119]
	ds_write_b64 v109, v[120:121]
	v_mad_u32_u24 v98, s19, 15, v88
	ds_write_b64 v98, v[116:117]
	s_waitcnt lgkmcnt(0)
	s_barrier
	s_cbranch_scc0 .LBB0_602
